# GLA scan: f32->bf16 pair packing by v_cvt_pk_bf16_f32 instead of the integer RNE sequence (on top of the in-place slot MFMAs)
# speedup vs baseline: 1.0039x; 1.0039x over previous
.LBB0_777:
	s_mul_i32 s10, s80, 0xab
	s_bfe_u32 s10, s10, 0x70009
	s_mul_i32 s10, s10, 3
	s_sub_i32 s10, s80, s10
	s_and_b32 s10, s10, 0xff
	v_lshl_add_u32 v16, s10, 12, v137
	ds_read_b128 v[124:127], v16
	ds_read_b128 v[120:123], v16 offset:1024
	ds_read_b128 v[116:119], v16 offset:2048
	ds_read_b128 v[112:115], v16 offset:3072
	v_cvt_pk_bf16_f32 v129, v2, v3
	v_cvt_pk_bf16_f32 v128, v0, v1
	v_cvt_pk_bf16_f32 v131, v6, v7
	v_cvt_pk_bf16_f32 v130, v4, v5
	v_cvt_pk_bf16_f32 v133, v10, v11
	v_cvt_pk_bf16_f32 v132, v8, v9
	v_cvt_pk_bf16_f32 v135, v14, v15
	v_cvt_pk_bf16_f32 v134, v12, v13
	s_waitcnt vmcnt(16)
	v_mfma_f32_32x32x16_bf16 v[16:31], v[104:107], v[128:131], 0
	s_and_b64 vcc, exec, s[4:5]
	s_waitcnt vmcnt(7)
	v_mfma_f32_32x32x16_bf16 v[16:31], v[108:111], v[132:135], v[16:31]
	s_cbranch_vccnz .LBB0_793
	s_mov_b64 s[10:11], -1
	s_and_b64 vcc, exec, s[44:45]
	s_cbranch_vccz .LBB0_790
	s_mov_b64 s[54:55], -1
	s_mov_b64 s[10:11], 0
	s_cmp_lt_i32 s65, 2
	s_mov_b64 s[12:13], 0
	s_cbranch_scc1 .LBB0_785
	s_cmp_eq_u32 s65, 2
	s_mov_b64 s[12:13], -1
	s_cbranch_scc0 .LBB0_782
	s_mov_b64 s[12:13], 0
	s_waitcnt vmcnt(4) lgkmcnt(1)
	s_nop 2
	v_mfma_f32_32x32x16_bf16 v[16:31], v[56:59], v[116:119], v[16:31]

.LBB0_813:
	s_waitcnt lgkmcnt(0)
	s_barrier
	ds_read2st64_b32 v[16:17], v239 offset1:1
	ds_read2st64_b32 v[18:19], v239 offset0:32 offset1:33
	ds_read2st64_b32 v[20:21], v239 offset0:64 offset1:65
	ds_read2st64_b32 v[22:23], v239 offset0:96 offset1:97
	ds_read2st64_b32 v[24:25], v239 offset0:128 offset1:129
	ds_read2st64_b32 v[26:27], v239 offset0:160 offset1:161
	ds_read2st64_b32 v[28:29], v239 offset0:192 offset1:193
	ds_read2st64_b32 v[30:31], v239 offset0:224 offset1:225
	s_waitcnt lgkmcnt(7)
	v_add_f32_e32 v16, 0, v16
	s_waitcnt lgkmcnt(6)
	v_add_f32_e32 v16, v16, v18
	s_waitcnt lgkmcnt(5)
	v_add_f32_e32 v16, v16, v20
	s_waitcnt lgkmcnt(4)
	v_add_f32_e32 v16, v16, v22
	s_waitcnt lgkmcnt(3)
	v_add_f32_e32 v16, v16, v24
	s_waitcnt lgkmcnt(2)
	v_add_f32_e32 v16, v16, v26
	s_waitcnt lgkmcnt(1)
	v_add_f32_e32 v16, v16, v28
	s_waitcnt lgkmcnt(0)
	v_add_f32_e32 v16, v16, v30
	v_bfe_u32 v18, v16, 16, 1
	v_add3_u32 v16, v16, v18, s31
	v_lshl_add_u64 v[32:33], s[96:97], 0, v[222:223]
	global_store_short_d16_hi v[32:33], v16, off
	v_add_f32_e32 v16, 0, v17
	v_add_f32_e32 v16, v16, v19
	v_add_f32_e32 v16, v16, v21
	v_add_f32_e32 v16, v16, v23
	v_add_f32_e32 v16, v16, v25
	v_add_f32_e32 v16, v16, v27
	v_add_f32_e32 v16, v16, v29
	v_add_f32_e32 v16, v16, v31
	v_bfe_u32 v17, v16, 16, 1
	v_add3_u32 v20, v16, v17, s31
	v_lshl_add_u64 v[16:17], s[96:97], 0, v[220:221]
	v_add_co_u32_e32 v18, vcc, s76, v16
	ds_read2st64_b32 v[22:23], v239 offset0:34 offset1:35
	ds_read2st64_b32 v[24:25], v239 offset0:66 offset1:67
	ds_read2st64_b32 v[26:27], v239 offset0:98 offset1:99
	v_addc_co_u32_e32 v19, vcc, 0, v17, vcc
	global_store_short_d16_hi v[18:19], v20, off offset:-4096
	ds_read2st64_b32 v[20:21], v239 offset0:2 offset1:3
	ds_read2st64_b32 v[28:29], v239 offset0:130 offset1:131
	ds_read2st64_b32 v[30:31], v239 offset0:162 offset1:163
	ds_read2st64_b32 v[32:33], v239 offset0:194 offset1:195
	ds_read2st64_b32 v[34:35], v239 offset0:226 offset1:227
	s_waitcnt lgkmcnt(4)
	v_add_f32_e32 v20, 0, v20
	v_add_f32_e32 v20, v20, v22
	v_add_f32_e32 v20, v20, v24
	v_add_f32_e32 v20, v20, v26
	s_waitcnt lgkmcnt(3)
	v_add_f32_e32 v20, v20, v28
	s_waitcnt lgkmcnt(2)
	v_add_f32_e32 v20, v20, v30
	s_waitcnt lgkmcnt(1)
	v_add_f32_e32 v20, v20, v32
	s_waitcnt lgkmcnt(0)
	v_add_f32_e32 v20, v20, v34
	v_bfe_u32 v22, v20, 16, 1
	v_add3_u32 v20, v20, v22, s31
	global_store_short_d16_hi v[18:19], v20, off
	v_add_f32_e32 v18, 0, v21
	v_add_f32_e32 v18, v18, v23
	v_add_f32_e32 v18, v18, v25
	v_add_f32_e32 v18, v18, v27
	v_add_f32_e32 v18, v18, v29
	v_add_f32_e32 v18, v18, v31
	v_add_f32_e32 v18, v18, v33
	v_add_f32_e32 v18, v18, v35
	s_mov_b32 s13, 0x2d403000
	v_bfe_u32 v19, v18, 16, 1
	v_add_co_u32_e32 v16, vcc, s13, v16
	v_add3_u32 v18, v18, v19, s31
	s_nop 0
	v_addc_co_u32_e32 v17, vcc, 0, v17, vcc
	global_store_short_d16_hi v[16:17], v18, off
	v_add_u32_e32 v16, s12, v137
	ds_read_b128 v[124:127], v16
	ds_read_b128 v[120:123], v16 offset:1024
	ds_read_b128 v[116:119], v16 offset:2048
	ds_read_b128 v[112:115], v16 offset:3072
	v_cvt_pk_bf16_f32 v129, v2, v3
	v_cvt_pk_bf16_f32 v128, v0, v1
	v_cvt_pk_bf16_f32 v131, v6, v7
	v_cvt_pk_bf16_f32 v130, v4, v5
	v_cvt_pk_bf16_f32 v133, v10, v11
	v_cvt_pk_bf16_f32 v132, v8, v9
	v_cvt_pk_bf16_f32 v135, v14, v15
	v_cvt_pk_bf16_f32 v134, v12, v13
	s_waitcnt vmcnt(16)
	v_mfma_f32_32x32x16_bf16 v[16:31], v[104:107], v[128:131], 0
	s_and_b64 vcc, exec, s[4:5]
	s_waitcnt vmcnt(15)
	v_mfma_f32_32x32x16_bf16 v[16:31], v[108:111], v[132:135], v[16:31]
	s_cbranch_vccnz .LBB0_829
	s_mov_b64 s[12:13], -1
	s_and_b64 vcc, exec, s[44:45]
	s_cbranch_vccz .LBB0_826
	s_mov_b64 s[60:61], -1
	s_mov_b64 s[12:13], 0
	s_cmp_lt_i32 s65, 2
	s_mov_b64 s[58:59], 0
	s_cbranch_scc1 .LBB0_821
	s_cmp_eq_u32 s65, 2
	s_mov_b64 s[58:59], -1
	s_cbranch_scc0 .LBB0_818
	s_mov_b64 s[58:59], 0
	s_waitcnt vmcnt(12) lgkmcnt(1)
	s_nop 2
	v_mfma_f32_32x32x16_bf16 v[16:31], v[56:59], v[116:119], v[16:31]
